# WY producer: loop-invariant per-lane parameters loaded once before the chunk loop; forward-substitution row chunks streamed through a 12-quad LDS prefetch ring (same FMA order)
# speedup vs baseline: 1.0144x; 1.0000x over previous
; #define LAS __attribute__((address_space(3)))
; __device__ __forceinline__ float bf2f(unsigned h) { return __uint_as_float(h << 16); }
; __device__ __forceinline__ void wy_issue(const Args& a, LAS unsigned char* stg, int b, int h, int c, int lane, float (&dec)[WY_T], float (&al)[WY_T], float (&rn)[WY_T]) {
;     ...
;     const size_t tok0 = (size_t)b * SEQ + (size_t)c * WY_T; const int ch = h * 64 + lane;
; #pragma unroll
;     for (int j = 0; j < 7; ++j) { const int idx = j * 64 + lane;
;         if (idx < 408) { const int row = idx >> 3, trel = row / 3, vec = row - 3 * trel; size_t tk = tok0 + trel; tk = (tk == 0) ? 1 : tk;
;             __builtin_amdgcn_global_load_lds((const unsigned*)(PR + (tk - 1) * 1792 + vec * 512 + h * 64 + (idx & 7) * 8), (LAS unsigned*)(stg + j * 1024), 16, 0, 0); } }
; #pragma unroll
;     for (int t = 0; t < WY_T; ++t) { dec[t] = DEC[(tok0 + t) * 512 + ch]; al[t] = bf2f(AL[(tok0 + t) * 512 + ch]); rn[t] = CT[(tok0 + t) * 8 + h]; }
.LBB0_1419:
	s_or_b64 exec, exec, s[0:1]
	s_cmpk_gt_u32 s90, 0x1ff
	s_cbranch_scc1 .LBB0_1382
	s_mul_i32 s0, s69, 0x4500
	s_add_i32 s89, s0, 0
	s_lshl_b32 s0, s4, 2
	v_readlane_b32 s2, v239, 62
	v_readlane_b32 s3, v239, 63
	s_add_u32 s91, s2, s0
	s_addc_u32 s68, s3, 0
	s_or_b32 s44, s92, 14
	s_mov_b32 s45, s93
	s_lshl_b64 s[0:1], s[44:45], 5
	s_add_u32 s0, s91, s0
	s_addc_u32 s1, s68, s1
	s_or_b32 s2, s92, 15
	s_mov_b32 s3, s93
	global_load_dword v36, v119, s[0:1]
	s_lshl_b64 s[0:1], s[2:3], 5
	s_add_u32 s0, s91, s0
	s_addc_u32 s1, s68, s1
	s_mov_b32 s81, s94
	v_or_b32_e32 v24, s80, v113
	global_load_dword v37, v119, s[0:1]
	s_lshl_b64 s[0:1], s[92:93], 9
	s_or_b32 s94, s92, 1
	s_mov_b32 s95, s93
	v_or_b32_e32 v0, s0, v24
	v_mov_b32_e32 v1, s1
	s_lshl_b64 s[0:1], s[94:95], 9
	v_or_b32_e32 v2, s0, v24
	v_mov_b32_e32 v3, s1
	v_lshl_add_u64 v[4:5], v[0:1], 1, s[60:61]
	v_lshl_add_u64 v[6:7], v[2:3], 1, s[60:61]
	global_load_ushort v6, v[6:7], off
	s_nop 0
	global_load_ushort v4, v[4:5], off
	s_or_b32 s96, s92, 2
	s_mov_b32 s97, s93
	s_lshl_b64 s[0:1], s[96:97], 9
	s_or_b32 vcc_lo, s92, 3
	s_mov_b32 vcc_hi, s93
	v_mov_b32_e32 v5, s1
	s_or_b32 s52, s92, 4
	s_mov_b32 s53, s93
	s_or_b32 s56, s92, 5
	s_mov_b32 s57, s93
	s_or_b32 s72, s92, 7
	s_mov_b32 s73, s93
	s_or_b32 s30, s92, 8
	s_mov_b32 s31, s93
	s_or_b32 s36, s92, 9
	s_mov_b32 s37, s93
	s_or_b32 s38, s92, 10
	s_mov_b32 s39, s93
	s_or_b32 s40, s92, 11
	s_mov_b32 s41, s93
	s_lshl_b64 s[2:3], s[2:3], 9
	s_lshl_b64 s[44:45], s[44:45], 9
	v_or_b32_e32 v46, s2, v24
	v_mov_b32_e32 v47, s3
	v_lshl_add_u64 v[48:49], v[46:47], 1, s[60:61]
	v_lshl_add_u64 v[0:1], v[0:1], 2, s[50:51]
	v_lshl_add_u64 v[2:3], v[2:3], 2, s[50:51]
	v_add_u32_e32 v79, s89, v198
	v_add_u32_e32 v83, s89, v221
	v_add_u32_e32 v229, s89, v201
	v_add_u32_e32 v230, s89, v202
	v_add_u32_e32 v231, s89, v203
	v_add_u32_e32 v232, s89, v204
	s_waitcnt vmcnt(0)
	v_lshlrev_b32_e32 v27, 16, v6
	v_lshlrev_b32_e32 v26, 16, v4
	v_or_b32_e32 v4, s0, v24
	s_lshl_b64 s[0:1], vcc, 9
	v_or_b32_e32 v6, s0, v24
	v_mov_b32_e32 v7, s1
	v_lshl_add_u64 v[8:9], v[4:5], 1, s[60:61]
	v_lshl_add_u64 v[10:11], v[6:7], 1, s[60:61]
	global_load_ushort v10, v[10:11], off
	s_nop 0
	global_load_ushort v8, v[8:9], off
	s_lshl_b64 s[0:1], s[52:53], 9
	v_mov_b32_e32 v9, s1
	s_waitcnt vmcnt(0)
	v_lshlrev_b32_e32 v29, 16, v10
	v_lshlrev_b32_e32 v28, 16, v8
	v_or_b32_e32 v8, s0, v24
	s_lshl_b64 s[0:1], s[56:57], 9
	v_or_b32_e32 v10, s0, v24
	v_mov_b32_e32 v11, s1
	v_lshl_add_u64 v[12:13], v[8:9], 1, s[60:61]
	v_lshl_add_u64 v[14:15], v[10:11], 1, s[60:61]
	global_load_ushort v14, v[14:15], off
	s_nop 0
	global_load_ushort v12, v[12:13], off
	s_or_b32 s0, s92, 6
	s_mov_b32 s1, s93
	s_lshl_b64 s[4:5], s[0:1], 9
	v_mov_b32_e32 v13, s5
	s_waitcnt vmcnt(0)
	v_lshlrev_b32_e32 v31, 16, v14
	v_lshlrev_b32_e32 v30, 16, v12
	v_or_b32_e32 v12, s4, v24
	s_lshl_b64 s[4:5], s[72:73], 9
	v_or_b32_e32 v14, s4, v24
	v_mov_b32_e32 v15, s5
	v_lshl_add_u64 v[16:17], v[12:13], 1, s[60:61]
	v_lshl_add_u64 v[18:19], v[14:15], 1, s[60:61]
	global_load_ushort v18, v[18:19], off
	s_nop 0
	global_load_ushort v16, v[16:17], off
	s_lshl_b64 s[4:5], s[30:31], 9
	v_mov_b32_e32 v17, s5
	s_waitcnt vmcnt(0)
	v_lshlrev_b32_e32 v33, 16, v18
	v_lshlrev_b32_e32 v32, 16, v16
	v_or_b32_e32 v16, s4, v24
	s_lshl_b64 s[4:5], s[36:37], 9
	v_or_b32_e32 v18, s4, v24
	v_mov_b32_e32 v19, s5
	v_lshl_add_u64 v[20:21], v[16:17], 1, s[60:61]
	v_lshl_add_u64 v[22:23], v[18:19], 1, s[60:61]
	global_load_ushort v22, v[22:23], off
	s_nop 0
	global_load_ushort v20, v[20:21], off
	s_lshl_b64 s[4:5], s[38:39], 9
	v_mov_b32_e32 v21, s5
	s_waitcnt vmcnt(0)
	v_lshlrev_b32_e32 v35, 16, v22
	v_lshlrev_b32_e32 v34, 16, v20
	v_or_b32_e32 v20, s4, v24
	s_lshl_b64 s[4:5], s[40:41], 9
	v_or_b32_e32 v22, s4, v24
	v_mov_b32_e32 v23, s5
	v_lshl_add_u64 v[38:39], v[20:21], 1, s[60:61]
	v_lshl_add_u64 v[40:41], v[22:23], 1, s[60:61]
	global_load_ushort v25, v[40:41], off
	s_nop 0
	global_load_ushort v38, v[38:39], off
	s_or_b32 s4, s92, 12
	s_mov_b32 s5, s93
	s_lshl_b64 s[34:35], s[4:5], 9
	v_mov_b32_e32 v39, s35
	s_mov_b32 s35, s93
	s_lshl_b64 s[2:3], s[4:5], 5
	v_readlane_b32 s4, v239, 38
	v_readlane_b32 s5, v239, 39
	v_readlane_b32 s16, v239, 50
	v_readlane_b32 s17, v239, 51
	v_readlane_b32 s18, v239, 52
	v_readlane_b32 s19, v239, 53
	v_readlane_b32 s6, v239, 40
	v_readlane_b32 s7, v239, 41
	v_readlane_b32 s8, v239, 42
	v_readlane_b32 s9, v239, 43
	v_readlane_b32 s10, v239, 44
	v_readlane_b32 s11, v239, 45
	v_readlane_b32 s12, v239, 46
	v_readlane_b32 s13, v239, 47
	v_readlane_b32 s14, v239, 48
	v_readlane_b32 s15, v239, 49
	s_waitcnt vmcnt(0)
; __device__ __forceinline__ float bf2f(unsigned h) { return __uint_as_float(h << 16); }
; __device__ __forceinline__ void wy_issue(const Args& a, LAS unsigned char* stg, int b, int h, int c, int lane, float (&dec)[WY_T], float (&al)[WY_T], float (&rn)[WY_T]) {
;     ...
;     for (int t = 0; t < WY_T; ++t) { dec[t] = DEC[(tok0 + t) * 512 + ch]; al[t] = bf2f(AL[(tok0 + t) * 512 + ch]); rn[t] = CT[(tok0 + t) * 8 + h]; }
; }
; __device__ __forceinline__ void wy_build1(const Args& a, LAS unsigned char* slot, const LAS unsigned char* stg, int h, int c, int lane, const float (&dec)[WY_T], const float (&alr)[WY_T], const float (&rn)[WY_T]) {
;     ...
;     const float mixr = ((const float*)a.in[16])[ch], mixk = ((const float*)a.in[16])[512 + ch], mixv = ((const float*)a.in[16])[1024 + ch];
;     const float k_k = ((const float*)a.in[22])[ch], k_a = ((const float*)a.in[23])[ch];
	v_lshlrev_b32_e32 v59, 16, v25
	v_lshlrev_b32_e32 v58, 16, v38
	v_or_b32_e32 v38, s34, v24
	s_or_b32 s34, s92, 13
	s_lshl_b64 s[82:83], s[34:35], 9
	v_or_b32_e32 v42, s82, v24
	v_mov_b32_e32 v43, s83
	v_lshl_add_u64 v[40:41], v[38:39], 1, s[60:61]
	v_lshl_add_u64 v[44:45], v[42:43], 1, s[60:61]
	global_load_ushort v25, v[44:45], off
	s_nop 0
	global_load_ushort v40, v[40:41], off
	v_mov_b32_e32 v41, s45
	s_add_u32 s2, s91, s2
	s_addc_u32 s3, s68, s3
	s_waitcnt vmcnt(0)
	v_lshlrev_b32_e32 v65, 16, v25
	v_lshlrev_b32_e32 v64, 16, v40
	v_or_b32_e32 v40, s44, v24
	v_lshl_add_u64 v[44:45], v[40:41], 1, s[60:61]
	global_load_ushort v25, v[48:49], off
	s_nop 0
	global_load_ushort v44, v[44:45], off
	s_waitcnt vmcnt(0)
	v_lshlrev_b32_e32 v77, 16, v25
	global_load_dword v74, v119, s[2:3]
	s_lshl_b64 s[2:3], s[34:35], 5
	s_add_u32 s2, s91, s2
	s_addc_u32 s3, s68, s3
	global_load_dword v75, v119, s[2:3]
	s_lshl_b64 s[2:3], s[38:39], 5
	s_add_u32 s2, s91, s2
	s_addc_u32 s3, s68, s3
	global_load_dword v72, v119, s[2:3]
	s_lshl_b64 s[2:3], s[40:41], 5
	s_add_u32 s2, s91, s2
	s_addc_u32 s3, s68, s3
	global_load_dword v73, v119, s[2:3]
	s_lshl_b64 s[2:3], s[30:31], 5
	s_add_u32 s2, s91, s2
	s_addc_u32 s3, s68, s3
	global_load_dword v70, v119, s[2:3]
	s_lshl_b64 s[2:3], s[36:37], 5
	s_add_u32 s2, s91, s2
	s_addc_u32 s3, s68, s3
	s_lshl_b64 s[0:1], s[0:1], 5
	s_add_u32 s0, s91, s0
	s_addc_u32 s1, s68, s1
	global_load_dword v71, v119, s[2:3]
	global_load_dword v68, v119, s[0:1]
	s_lshl_b64 s[0:1], s[72:73], 5
	s_add_u32 s0, s91, s0
	s_addc_u32 s1, s68, s1
	global_load_dword v0, v[0:1], off
	v_lshlrev_b32_e32 v76, 16, v44
	global_load_dword v69, v119, s[0:1]
	s_lshl_b64 s[0:1], s[52:53], 5
	s_add_u32 s0, s91, s0
	s_addc_u32 s1, s68, s1
	global_load_dword v1, v[2:3], off
	global_load_dword v66, v119, s[0:1]
	s_lshl_b64 s[0:1], s[56:57], 5
	s_add_u32 s0, s91, s0
	v_lshl_add_u64 v[2:3], v[4:5], 2, s[50:51]
	s_addc_u32 s1, s68, s1
	global_load_dword v2, v[2:3], off
	v_lshl_add_u64 v[4:5], v[6:7], 2, s[50:51]
	global_load_dword v67, v119, s[0:1]
	s_lshl_b64 s[0:1], s[96:97], 5
	s_add_u32 s0, s91, s0
	s_addc_u32 s1, s68, s1
	global_load_dword v3, v[4:5], off
	global_load_dword v62, v119, s[0:1]
	s_lshl_b64 s[0:1], vcc, 5
	s_add_u32 s0, s91, s0
	v_lshl_add_u64 v[4:5], v[8:9], 2, s[50:51]
	s_addc_u32 s1, s68, s1
	global_load_dword v4, v[4:5], off
	v_lshl_add_u64 v[6:7], v[10:11], 2, s[50:51]
	global_load_dword v63, v119, s[0:1]
	s_lshl_b64 s[0:1], s[92:93], 5
	s_add_u32 s0, s91, s0
	s_addc_u32 s1, s68, s1
	global_load_dword v5, v[6:7], off
	global_load_dword v60, v119, s[0:1]
	s_lshl_b64 s[0:1], s[94:95], 5
	s_add_u32 s0, s91, s0
	v_lshl_add_u64 v[6:7], v[12:13], 2, s[50:51]
	v_lshl_add_u64 v[8:9], v[14:15], 2, s[50:51]
	s_addc_u32 s1, s68, s1
	global_load_dword v6, v[6:7], off
	v_lshl_add_u64 v[10:11], v[18:19], 2, s[50:51]
	global_load_dword v61, v119, s[0:1]
	global_load_dword v7, v[8:9], off
	v_lshl_add_u64 v[8:9], v[16:17], 2, s[50:51]
	global_load_dword v8, v[8:9], off
	v_lshl_add_u64 v[12:13], v[22:23], 2, s[50:51]
	global_load_dword v9, v[10:11], off
	v_lshl_add_u64 v[10:11], v[20:21], 2, s[50:51]
	global_load_dword v10, v[10:11], off
	v_lshl_add_u64 v[14:15], v[42:43], 2, s[50:51]
	global_load_dword v11, v[12:13], off
	v_lshl_add_u64 v[12:13], v[38:39], 2, s[50:51]
	global_load_dword v12, v[12:13], off
	v_lshl_add_u64 v[16:17], v[46:47], 2, s[50:51]
	global_load_dword v13, v[14:15], off
	v_lshl_add_u64 v[14:15], v[40:41], 2, s[50:51]
	global_load_dword v14, v[14:15], off
	s_lshl_b32 s0, s69, 2
	global_load_dword v15, v[16:17], off
	v_lshlrev_b32_e32 v16, 2, v24
	v_mov_b32_e32 v17, v119
	v_add_u32_e32 v18, s89, v199
	s_add_i32 s2, s0, 0
	s_lshl_b32 s92, s80, 1
	s_mov_b32 s93, s85
	v_lshl_add_u64 v[40:41], s[4:5], 0, v[16:17]
	s_mov_b64 s[0:1], 0x1000
	v_lshl_add_u32 v25, v113, 1, s88
	s_add_i32 s2, s2, 0x19e00
	v_lshl_add_u64 v[38:39], v[138:139], 0, s[92:93]
	v_lshl_add_u64 v[42:43], v[40:41], 0, s[0:1]
	v_lshl_add_u64 v[44:45], s[16:17], 0, v[16:17]
	v_lshl_add_u64 v[46:47], s[18:19], 0, v[16:17]
	v_lshl_add_u64 v[48:49], v[150:151], 0, s[92:93]
	v_lshl_add_u64 v[50:51], v[152:153], 0, s[92:93]
	v_lshl_add_u64 v[52:53], v[154:155], 0, s[92:93]
	v_lshl_add_u64 v[54:55], v[156:157], 0, s[92:93]
	v_lshl_add_u64 v[56:57], v[158:159], 0, s[92:93]
	v_add_u32_e32 v85, v18, v200
	s_add_i32 s3, s88, 0x800
	s_add_i32 s4, s88, 0x1400
	global_load_dword v120, v[40:41], off
	global_load_dword v224, v[40:41], off offset:2048
	global_load_dword v226, v[46:47], off
	global_load_dword v112, v[44:45], off
	global_load_dword v116, v[42:43], off
	s_branch .LBB0_1422

; #define LAS __attribute__((address_space(3)))
; __device__ __forceinline__ float bf2f(unsigned h) { return __uint_as_float(h << 16); }
; __device__ __forceinline__ void wy_build1(const Args& a, LAS unsigned char* slot, const LAS unsigned char* stg, int h, int c, int lane, const float (&dec)[WY_T], const float (&alr)[WY_T], const float (&rn)[WY_T]) {
;     ...
;         const f32x2 cr = {bf2f(sg[(3 * (t + 1)) * 64]), bf2f(sg[(3 * (t + 2)) * 64])}, ck = {bf2f(sg[(3 * (t + 1) + 1) * 64]), bf2f(sg[(3 * (t + 2) + 1) * 64])}, cv = {bf2f(sg[(3 * (t + 1) + 2) * 64]), bf2f(sg[(3 * (t + 2) + 2) * 64])};
;         const f32x2 prv = {pr, cr.x}, pkv = {pk, ck.x}, pvw = {pvv, cv.x};
;         const f32x2 w = {dec[t], dec[t + 1]}, al = {alr[t], alr[t + 1]}, rnv = {rn[t], rn[t + 1]};
;         const f32x2 r = cr + (prv - cr) * mixr, kx = ck + (pkv - ck) * mixk, vxx = cv + (pvw - cv) * mixv; pr = cr.y; pk = ck.y; pvv = cv.y;
;         vx[t] = vxx.x; vx[t + 1] = vxx.y;
;         const f32x2 kkn = kx * k_k * rnv, bvv = kkn * al, kvv = kx * ((al - 1.f) * k_a + 1.f);
;         bv[t] = bvv.x; bv[t + 1] = bvv.y; kv[t] = kvv.x; kv[t + 1] = kvv.y;
;         const float P0 = Pcum * w.x, P1 = P0 * w.y; const f32x2 Pprev = {Pcum, P0}, Pc = {P0, P1}; Pcum = P1;
;         f32x2 invP; invP.x = __builtin_amdgcn_rcpf(P0); invP.y = __builtin_amdgcn_rcpf(P1); Pt[t] = invP.x; Pt[t + 1] = invP.y;
;         const f32x2 az = -(kkn * Pprev), ay = r * Pc, bt = bvv * invP, kt2 = kvv * invP;
;         const unsigned waz = pk2(az.x, az.y), way = pk2(ay.x, ay.y), wbt = pk2(bt.x, bt.y), wkt = pk2(kt2.x, kt2.y);
;         const int po = po0 + t * 64;
;         *(LAS unsigned short*)(slot + WY_AZ + po) = (unsigned short)waz; *(LAS unsigned short*)(slot + WY_AZ + po + 64) = (unsigned short)(waz >> 16);
;         *(LAS unsigned short*)(slot + WY_AY1 + po) = (unsigned short)way; *(LAS unsigned short*)(slot + WY_AY1 + po + 64) = (unsigned short)(way >> 16);
;         *(LAS unsigned short*)(scr + po) = (unsigned short)wbt; *(LAS unsigned short*)(scr + po + 64) = (unsigned short)(wbt >> 16);
;         *(LAS unsigned short*)(scr + 2048 + po) = (unsigned short)wkt; *(LAS unsigned short*)(scr + 2048 + po + 64) = (unsigned short)(wkt >> 16);
.LBB0_1424:
	s_waitcnt vmcnt(0)
	ds_read_u16 v16, v25 offset:384
	ds_read_u16 v17, v25 offset:768
	s_waitcnt vmcnt(20)
	v_mul_f32_e32 v23, v0, v1
	v_mov_b32_e32 v22, v0
	s_waitcnt vmcnt(18)
	v_mul_f32_e32 v93, v2, v23
	s_waitcnt lgkmcnt(1)
	v_lshlrev_b32_e32 v20, 16, v16
	s_waitcnt lgkmcnt(0)
	v_lshlrev_b32_e32 v21, 16, v17
	ds_read_u16 v16, v25 offset:512
	ds_read_u16 v17, v25 offset:896
	v_mov_b32_e32 v19, v20
	v_mov_b32_e32 v92, v23
	v_pk_add_f32 v[80:81], v[26:27], -1.0 op_sel_hi:[1,0]
	s_waitcnt lgkmcnt(1)
	v_lshlrev_b32_e32 v90, 16, v16
	s_waitcnt lgkmcnt(0)
	v_lshlrev_b32_e32 v91, 16, v17
	ds_read_u16 v16, v25 offset:640
	ds_read_u16 v17, v25 offset:1024
	ds_read_u16 v18, v25
	ds_read_u16 v194, v25 offset:256
	v_xor_b32_e32 v161, 0x80000000, v0
	v_mov_b32_e32 v98, v21
	v_pk_add_f32 v[100:101], v[28:29], -1.0 op_sel_hi:[1,0]
	s_waitcnt lgkmcnt(1)
	v_lshlrev_b32_e32 v18, 16, v18
	v_pk_add_f32 v[18:19], v[18:19], v[20:21] neg_lo:[0,1] neg_hi:[0,1]
	v_lshlrev_b32_e32 v16, 16, v16
	v_lshlrev_b32_e32 v17, 16, v17
	s_waitcnt lgkmcnt(0)
	v_lshlrev_b32_e32 v194, 16, v194
	v_mov_b32_e32 v195, v16
	v_pk_add_f32 v[194:195], v[194:195], v[16:17] neg_lo:[0,1] neg_hi:[0,1]
	s_add_i32 s84, s90, 6
	s_cmpk_gt_i32 s90, 0x1f9
	s_cselect_b64 s[94:95], -1, 0
	s_and_b64 vcc, exec, s[94:95]
	s_waitcnt vmcnt(1)
	v_pk_fma_f32 v[18:19], v[120:121], v[18:19], v[20:21] op_sel_hi:[0,1,1]
	v_pk_mul_f32 v[18:19], v[22:23], v[18:19]
	v_cvt_pk_bf16_f32 v84, v18, v19
	ds_read_u16 v18, v25 offset:128
	ds_write_b16 v79, v84 offset:2048
	ds_write_b16_d16_hi v79, v84 offset:2112
	v_rcp_f32_e32 v23, v23
	v_rcp_f32_e32 v22, v0
	s_waitcnt lgkmcnt(2)
	v_lshlrev_b32_e32 v18, 16, v18
	v_mov_b32_e32 v19, v90
	v_pk_add_f32 v[18:19], v[18:19], v[90:91] neg_lo:[0,1] neg_hi:[0,1]
	s_waitcnt vmcnt(1)
	v_pk_fma_f32 v[80:81], v[80:81], v[226:227], 1.0 op_sel_hi:[1,0,0]
	v_pk_fma_f32 v[18:19], v[224:225], v[18:19], v[90:91] op_sel_hi:[0,1,1]
	v_pk_mul_f32 v[80:81], v[80:81], v[18:19]
	v_mov_b32_e32 v90, v91
	s_waitcnt vmcnt(0)
	v_pk_mul_f32 v[18:19], v[112:113], v[18:19] op_sel_hi:[0,1]
	v_pk_mul_f32 v[86:87], v[22:23], v[80:81]
	v_pk_mul_f32 v[18:19], v[60:61], v[18:19]
	v_cvt_pk_bf16_f32 v88, v86, v87
	v_pk_mul_f32 v[86:87], v[160:161], v[18:19]
	ds_write_b16 v79, v88 offset:14592
	ds_write_b16_d16_hi v79, v88 offset:14656
	v_cvt_pk_bf16_f32 v89, v86, v87
	v_pk_mul_f32 v[86:87], v[26:27], v[18:19]
	v_mov_b32_e32 v88, v93
	v_pk_mul_f32 v[18:19], v[22:23], v[86:87]
	s_nop 0
	v_cvt_pk_bf16_f32 v18, v18, v19
	ds_write_b16 v79, v89
	ds_write_b16_d16_hi v79, v89 offset:64
	ds_write_b16 v79, v18 offset:12544
	ds_write_b16_d16_hi v79, v18 offset:12608
	ds_read_u16 v18, v25 offset:1152
	ds_read_u16 v19, v25 offset:1536
	v_mul_f32_e32 v89, v3, v93
	s_waitcnt lgkmcnt(1)
	v_lshlrev_b32_e32 v94, 16, v18
	s_waitcnt lgkmcnt(0)
	v_lshlrev_b32_e32 v95, 16, v19
	ds_read_u16 v18, v25 offset:1280
	ds_read_u16 v19, v25 offset:1664
	v_mov_b32_e32 v99, v94
	v_pk_add_f32 v[98:99], v[98:99], v[94:95] neg_lo:[0,1] neg_hi:[0,1]
	s_waitcnt lgkmcnt(1)
	v_lshlrev_b32_e32 v96, 16, v18
	v_pk_fma_f32 v[98:99], v[120:121], v[98:99], v[94:95] op_sel_hi:[0,1,1]
	v_pk_mul_f32 v[98:99], v[88:89], v[98:99]
	s_waitcnt lgkmcnt(0)
	v_lshlrev_b32_e32 v97, 16, v19
	v_cvt_pk_bf16_f32 v21, v98, v99
	v_mul_f32_e32 v99, v4, v89
	v_mov_b32_e32 v98, v89
	v_rcp_f32_e32 v89, v89
	v_rcp_f32_e32 v88, v93
	v_mov_b32_e32 v91, v96
	v_pk_add_f32 v[90:91], v[90:91], v[96:97] neg_lo:[0,1] neg_hi:[0,1]
	v_pk_fma_f32 v[100:101], v[100:101], v[226:227], 1.0 op_sel_hi:[1,0,0]
	v_pk_fma_f32 v[102:103], v[224:225], v[90:91], v[96:97] op_sel_hi:[0,1,1]
	v_pk_mul_f32 v[90:91], v[100:101], v[102:103]
	ds_read_u16 v18, v25 offset:1408
	ds_read_u16 v19, v25 offset:1792
	v_pk_mul_f32 v[100:101], v[88:89], v[90:91]
	ds_write_b16 v79, v21 offset:2176
	ds_write_b16_d16_hi v79, v21 offset:2240
	v_cvt_pk_bf16_f32 v94, v100, v101
	v_pk_mul_f32 v[100:101], v[112:113], v[102:103] op_sel_hi:[0,1]
	v_pk_mul_f32 v[100:101], v[62:63], v[100:101]
	s_waitcnt lgkmcnt(3)
	v_lshlrev_b32_e32 v18, 16, v18
	v_pk_mul_f32 v[92:93], v[100:101], v[92:93] neg_lo:[0,1] neg_hi:[0,1]
	s_waitcnt lgkmcnt(2)
	v_lshlrev_b32_e32 v19, 16, v19
	v_cvt_pk_bf16_f32 v21, v92, v93
	v_pk_mul_f32 v[92:93], v[28:29], v[100:101]
	s_nop 0
	v_pk_mul_f32 v[100:101], v[88:89], v[92:93]
	s_nop 0
	v_cvt_pk_bf16_f32 v96, v100, v101
	ds_write_b16 v79, v21 offset:128
	ds_write_b16_d16_hi v79, v21 offset:192
	ds_write_b16 v79, v96 offset:12672
	ds_write_b16_d16_hi v79, v96 offset:12736
	ds_write_b16 v79, v94 offset:14720
	ds_write_b16_d16_hi v79, v94 offset:14784
	ds_read_u16 v21, v25 offset:1920
	ds_read_u16 v94, v25 offset:2304
	v_mov_b32_e32 v96, v97
	s_waitcnt lgkmcnt(1)
	v_lshlrev_b32_e32 v100, 16, v21
	s_waitcnt lgkmcnt(0)
	v_lshlrev_b32_e32 v101, 16, v94
	ds_read_u16 v21, v25 offset:2048
	ds_read_u16 v94, v25 offset:2432
	s_waitcnt lgkmcnt(1)
	v_lshlrev_b32_e32 v102, 16, v21
	s_waitcnt lgkmcnt(0)
	v_lshlrev_b32_e32 v103, 16, v94
	ds_read_u16 v21, v25 offset:2176
	ds_read_u16 v94, v25 offset:2560
	v_mov_b32_e32 v97, v102
	s_waitcnt lgkmcnt(1)
	v_lshlrev_b32_e32 v182, 16, v21
	s_waitcnt lgkmcnt(0)
; #define LAS __attribute__((address_space(3)))
; __device__ __forceinline__ float bf2f(unsigned h) { return __uint_as_float(h << 16); }
; __device__ __forceinline__ void wy_build1(const Args& a, LAS unsigned char* slot, const LAS unsigned char* stg, int h, int c, int lane, const float (&dec)[WY_T], const float (&alr)[WY_T], const float (&rn)[WY_T]) {
;     ...
;         const f32x2 cr = {bf2f(sg[(3 * (t + 1)) * 64]), bf2f(sg[(3 * (t + 2)) * 64])}, ck = {bf2f(sg[(3 * (t + 1) + 1) * 64]), bf2f(sg[(3 * (t + 2) + 1) * 64])}, cv = {bf2f(sg[(3 * (t + 1) + 2) * 64]), bf2f(sg[(3 * (t + 2) + 2) * 64])};
;         const f32x2 prv = {pr, cr.x}, pkv = {pk, ck.x}, pvw = {pvv, cv.x};
;         const f32x2 w = {dec[t], dec[t + 1]}, al = {alr[t], alr[t + 1]}, rnv = {rn[t], rn[t + 1]};
;         const f32x2 r = cr + (prv - cr) * mixr, kx = ck + (pkv - ck) * mixk, vxx = cv + (pvw - cv) * mixv; pr = cr.y; pk = ck.y; pvv = cv.y;
;         vx[t] = vxx.x; vx[t + 1] = vxx.y;
;         const f32x2 kkn = kx * k_k * rnv, bvv = kkn * al, kvv = kx * ((al - 1.f) * k_a + 1.f);
;         bv[t] = bvv.x; bv[t + 1] = bvv.y; kv[t] = kvv.x; kv[t + 1] = kvv.y;
;         const float P0 = Pcum * w.x, P1 = P0 * w.y; const f32x2 Pprev = {Pcum, P0}, Pc = {P0, P1}; Pcum = P1;
;         f32x2 invP; invP.x = __builtin_amdgcn_rcpf(P0); invP.y = __builtin_amdgcn_rcpf(P1); Pt[t] = invP.x; Pt[t + 1] = invP.y;
;         const f32x2 az = -(kkn * Pprev), ay = r * Pc, bt = bvv * invP, kt2 = kvv * invP;
;         const unsigned waz = pk2(az.x, az.y), way = pk2(ay.x, ay.y), wbt = pk2(bt.x, bt.y), wkt = pk2(kt2.x, kt2.y);
;         const int po = po0 + t * 64;
;         *(LAS unsigned short*)(slot + WY_AZ + po) = (unsigned short)waz; *(LAS unsigned short*)(slot + WY_AZ + po + 64) = (unsigned short)(waz >> 16);
;         *(LAS unsigned short*)(slot + WY_AY1 + po) = (unsigned short)way; *(LAS unsigned short*)(slot + WY_AY1 + po + 64) = (unsigned short)(way >> 16);
;         *(LAS unsigned short*)(scr + po) = (unsigned short)wbt; *(LAS unsigned short*)(scr + po + 64) = (unsigned short)(wbt >> 16);
;         *(LAS unsigned short*)(scr + 2048 + po) = (unsigned short)wkt; *(LAS unsigned short*)(scr + 2048 + po + 64) = (unsigned short)(wkt >> 16);
	v_lshlrev_b32_e32 v183, 16, v94
	v_mov_b32_e32 v94, v95
	v_mov_b32_e32 v95, v100
	v_pk_add_f32 v[94:95], v[94:95], v[100:101] neg_lo:[0,1] neg_hi:[0,1]
	s_nop 0
	v_pk_fma_f32 v[104:105], v[120:121], v[94:95], v[100:101] op_sel_hi:[0,1,1]
	v_pk_add_f32 v[94:95], v[96:97], v[102:103] neg_lo:[0,1] neg_hi:[0,1]
	s_nop 0
	v_pk_fma_f32 v[96:97], v[224:225], v[94:95], v[102:103] op_sel_hi:[0,1,1]
	v_pk_add_f32 v[94:95], v[30:31], -1.0 op_sel_hi:[1,0]
	s_nop 0
	v_pk_fma_f32 v[94:95], v[94:95], v[226:227], 1.0 op_sel_hi:[1,0,0]
	s_nop 0
	v_pk_mul_f32 v[94:95], v[94:95], v[96:97]
	v_pk_mul_f32 v[96:97], v[112:113], v[96:97] op_sel_hi:[0,1]
	v_pk_mul_f32 v[106:107], v[66:67], v[96:97]
	v_mul_f32_e32 v97, v5, v99
	v_mov_b32_e32 v96, v99
	v_pk_mul_f32 v[104:105], v[96:97], v[104:105]
	v_mul_f32_e32 v109, v6, v97
	v_mov_b32_e32 v108, v97
	v_rcp_f32_e32 v97, v97
	v_rcp_f32_e32 v96, v99
	v_pk_mul_f32 v[98:99], v[106:107], v[98:99] neg_lo:[0,1] neg_hi:[0,1]
	v_cvt_pk_bf16_f32 v100, v104, v105
	v_cvt_pk_bf16_f32 v21, v98, v99
	v_pk_mul_f32 v[98:99], v[30:31], v[106:107]
	s_nop 0
	v_pk_mul_f32 v[104:105], v[96:97], v[98:99]
	s_nop 0
	v_cvt_pk_bf16_f32 v102, v104, v105
	v_pk_mul_f32 v[104:105], v[96:97], v[94:95]
	s_nop 0
	v_cvt_pk_bf16_f32 v104, v104, v105
	ds_write_b16 v79, v21 offset:256
	ds_write_b16_d16_hi v79, v21 offset:320
	ds_write_b16 v79, v100 offset:2304
	ds_write_b16_d16_hi v79, v100 offset:2368
	ds_write_b16 v79, v102 offset:12800
	ds_write_b16_d16_hi v79, v102 offset:12864
	ds_write_b16 v79, v104 offset:14848
	ds_write_b16_d16_hi v79, v104 offset:14912
	ds_read_u16 v21, v25 offset:2688
	ds_read_u16 v100, v25 offset:3072
	v_mov_b32_e32 v102, v103
	s_waitcnt lgkmcnt(1)
	v_lshlrev_b32_e32 v106, 16, v21
	s_waitcnt lgkmcnt(0)
	v_lshlrev_b32_e32 v107, 16, v100
	ds_read_u16 v21, v25 offset:2816
	ds_read_u16 v100, v25 offset:3200
	s_waitcnt lgkmcnt(1)
	v_lshlrev_b32_e32 v110, 16, v21
	s_waitcnt lgkmcnt(0)
	v_lshlrev_b32_e32 v111, 16, v100
	ds_read_u16 v21, v25 offset:2944
	ds_read_u16 v100, v25 offset:3328
	v_mov_b32_e32 v103, v110
	s_waitcnt lgkmcnt(1)
	v_lshlrev_b32_e32 v184, 16, v21
	s_waitcnt lgkmcnt(0)
	v_lshlrev_b32_e32 v185, 16, v100
	v_mov_b32_e32 v100, v101
	v_mov_b32_e32 v101, v106
	v_pk_add_f32 v[100:101], v[100:101], v[106:107] neg_lo:[0,1] neg_hi:[0,1]
	s_nop 0
	v_pk_fma_f32 v[104:105], v[120:121], v[100:101], v[106:107] op_sel_hi:[0,1,1]
	v_pk_add_f32 v[100:101], v[102:103], v[110:111] neg_lo:[0,1] neg_hi:[0,1]
	s_nop 0
	v_pk_fma_f32 v[102:103], v[224:225], v[100:101], v[110:111] op_sel_hi:[0,1,1]
	v_pk_add_f32 v[100:101], v[32:33], -1.0 op_sel_hi:[1,0]
	s_nop 0
	v_pk_fma_f32 v[100:101], v[100:101], v[226:227], 1.0 op_sel_hi:[1,0,0]
	s_nop 0
	v_pk_mul_f32 v[100:101], v[100:101], v[102:103]
	v_pk_mul_f32 v[102:103], v[112:113], v[102:103] op_sel_hi:[0,1]
	v_pk_mul_f32 v[162:163], v[68:69], v[102:103]
	v_mul_f32_e32 v103, v7, v109
	v_mov_b32_e32 v102, v109
	v_pk_mul_f32 v[104:105], v[102:103], v[104:105]
	v_mul_f32_e32 v167, v8, v103
	v_mov_b32_e32 v166, v103
	v_rcp_f32_e32 v103, v103
	v_rcp_f32_e32 v102, v109
	v_pk_mul_f32 v[108:109], v[162:163], v[108:109] neg_lo:[0,1] neg_hi:[0,1]
	v_cvt_pk_bf16_f32 v106, v104, v105
	v_pk_mul_f32 v[104:105], v[32:33], v[162:163]
	v_cvt_pk_bf16_f32 v21, v108, v109
	v_pk_mul_f32 v[108:109], v[102:103], v[104:105]
	s_nop 0
	v_cvt_pk_bf16_f32 v110, v108, v109
	v_pk_mul_f32 v[108:109], v[102:103], v[100:101]
	s_nop 0
	v_cvt_pk_bf16_f32 v108, v108, v109
	ds_write_b16 v79, v21 offset:384
	ds_write_b16_d16_hi v79, v21 offset:448
	ds_write_b16 v79, v106 offset:2432
	ds_write_b16_d16_hi v79, v106 offset:2496
	ds_write_b16 v79, v110 offset:12928
	ds_write_b16_d16_hi v79, v110 offset:12992
	ds_write_b16 v79, v108 offset:14976
	ds_write_b16_d16_hi v79, v108 offset:15040
	ds_read_u16 v21, v25 offset:3456
	ds_read_u16 v106, v25 offset:3840
	v_mov_b32_e32 v108, v111
	s_waitcnt lgkmcnt(1)
	v_lshlrev_b32_e32 v162, 16, v21
	s_waitcnt lgkmcnt(0)
	v_lshlrev_b32_e32 v163, 16, v106
	ds_read_u16 v21, v25 offset:3584
	ds_read_u16 v106, v25 offset:3968
	s_waitcnt lgkmcnt(1)
	v_lshlrev_b32_e32 v168, 16, v21
	s_waitcnt lgkmcnt(0)
	v_lshlrev_b32_e32 v169, 16, v106
	ds_read_u16 v21, v25 offset:3712
	ds_read_u16 v106, v25 offset:4096
	v_mov_b32_e32 v109, v168
	s_waitcnt lgkmcnt(1)
	v_lshlrev_b32_e32 v186, 16, v21
	s_waitcnt lgkmcnt(0)
	v_lshlrev_b32_e32 v187, 16, v106
	v_mov_b32_e32 v106, v107
	v_mov_b32_e32 v107, v162
	v_pk_add_f32 v[106:107], v[106:107], v[162:163] neg_lo:[0,1] neg_hi:[0,1]
	s_nop 0
	v_pk_fma_f32 v[110:111], v[120:121], v[106:107], v[162:163] op_sel_hi:[0,1,1]
	v_pk_add_f32 v[106:107], v[108:109], v[168:169] neg_lo:[0,1] neg_hi:[0,1]
	s_nop 0
	v_pk_fma_f32 v[108:109], v[224:225], v[106:107], v[168:169] op_sel_hi:[0,1,1]
	v_pk_add_f32 v[106:107], v[34:35], -1.0 op_sel_hi:[1,0]
	s_nop 0
	v_pk_fma_f32 v[106:107], v[106:107], v[226:227], 1.0 op_sel_hi:[1,0,0]
	s_nop 0
	v_pk_mul_f32 v[106:107], v[106:107], v[108:109]
	v_pk_mul_f32 v[108:109], v[112:113], v[108:109] op_sel_hi:[0,1]
	v_pk_mul_f32 v[170:171], v[70:71], v[108:109]
	v_mul_f32_e32 v109, v9, v167
	v_mov_b32_e32 v108, v167
	v_pk_mul_f32 v[110:111], v[108:109], v[110:111]
	v_mul_f32_e32 v173, v10, v109
	v_mov_b32_e32 v172, v109
	v_rcp_f32_e32 v109, v109
	v_rcp_f32_e32 v108, v167
	v_pk_mul_f32 v[166:167], v[170:171], v[166:167] neg_lo:[0,1] neg_hi:[0,1]
	v_cvt_pk_bf16_f32 v161, v110, v111
	v_pk_mul_f32 v[110:111], v[34:35], v[170:171]
	v_cvt_pk_bf16_f32 v21, v166, v167
	v_pk_mul_f32 v[166:167], v[108:109], v[110:111]
	s_nop 0
	v_cvt_pk_bf16_f32 v162, v166, v167
	v_pk_mul_f32 v[166:167], v[108:109], v[106:107]
	s_nop 0
	v_cvt_pk_bf16_f32 v166, v166, v167
	ds_write_b16 v79, v21 offset:512
	ds_write_b16_d16_hi v79, v21 offset:576
	ds_write_b16 v79, v161 offset:2560
	ds_write_b16_d16_hi v79, v161 offset:2624
	ds_write_b16 v79, v162 offset:13056
	ds_write_b16_d16_hi v79, v162 offset:13120
	ds_write_b16 v79, v166 offset:15104
	ds_write_b16_d16_hi v79, v166 offset:15168
	ds_read_u16 v21, v25 offset:4224
	ds_read_u16 v161, v25 offset:4608
	v_mov_b32_e32 v162, v163
	v_mov_b32_e32 v166, v169
	s_waitcnt lgkmcnt(1)
; #define LAS __attribute__((address_space(3)))
; __device__ __forceinline__ void wy_build1(const Args& a, LAS unsigned char* slot, const LAS unsigned char* stg, int h, int c, int lane, const float (&dec)[WY_T], const float (&alr)[WY_T], const float (&rn)[WY_T]) {
;     ...
;         const f32x2 cr = {bf2f(sg[(3 * (t + 1)) * 64]), bf2f(sg[(3 * (t + 2)) * 64])}, ck = {bf2f(sg[(3 * (t + 1) + 1) * 64]), bf2f(sg[(3 * (t + 2) + 1) * 64])}, cv = {bf2f(sg[(3 * (t + 1) + 2) * 64]), bf2f(sg[(3 * (t + 2) + 2) * 64])};
;         const f32x2 prv = {pr, cr.x}, pkv = {pk, ck.x}, pvw = {pvv, cv.x};
;         const f32x2 w = {dec[t], dec[t + 1]}, al = {alr[t], alr[t + 1]}, rnv = {rn[t], rn[t + 1]};
;         const f32x2 r = cr + (prv - cr) * mixr, kx = ck + (pkv - ck) * mixk, vxx = cv + (pvw - cv) * mixv; pr = cr.y; pk = ck.y; pvv = cv.y;
;         vx[t] = vxx.x; vx[t + 1] = vxx.y;
;         const f32x2 kkn = kx * k_k * rnv, bvv = kkn * al, kvv = kx * ((al - 1.f) * k_a + 1.f);
;         bv[t] = bvv.x; bv[t + 1] = bvv.y; kv[t] = kvv.x; kv[t + 1] = kvv.y;
;         const float P0 = Pcum * w.x, P1 = P0 * w.y; const f32x2 Pprev = {Pcum, P0}, Pc = {P0, P1}; Pcum = P1;
;         f32x2 invP; invP.x = __builtin_amdgcn_rcpf(P0); invP.y = __builtin_amdgcn_rcpf(P1); Pt[t] = invP.x; Pt[t + 1] = invP.y;
;         const f32x2 az = -(kkn * Pprev), ay = r * Pc, bt = bvv * invP, kt2 = kvv * invP;
;         const unsigned waz = pk2(az.x, az.y), way = pk2(ay.x, ay.y), wbt = pk2(bt.x, bt.y), wkt = pk2(kt2.x, kt2.y);
;         const int po = po0 + t * 64;
;         *(LAS unsigned short*)(slot + WY_AZ + po) = (unsigned short)waz; *(LAS unsigned short*)(slot + WY_AZ + po + 64) = (unsigned short)(waz >> 16);
;         *(LAS unsigned short*)(slot + WY_AY1 + po) = (unsigned short)way; *(LAS unsigned short*)(slot + WY_AY1 + po + 64) = (unsigned short)(way >> 16);
;         *(LAS unsigned short*)(scr + po) = (unsigned short)wbt; *(LAS unsigned short*)(scr + po + 64) = (unsigned short)(wbt >> 16);
;         *(LAS unsigned short*)(scr + 2048 + po) = (unsigned short)wkt; *(LAS unsigned short*)(scr + 2048 + po + 64) = (unsigned short)(wkt >> 16);
;     }
;     { u32x4 w0, w1; w0.x = pk2(vx[0], vx[1]); w0.y = pk2(vx[2], vx[3]); w0.z = pk2(vx[4], vx[5]); w0.w = pk2(vx[6], vx[7]); w1.x = pk2(vx[8], vx[9]); w1.y = pk2(vx[10], vx[11]); w1.z = pk2(vx[12], vx[13]); w1.w = pk2(vx[14], vx[15]);
	v_lshlrev_b32_e32 v170, 16, v21
	s_waitcnt lgkmcnt(0)
	v_lshlrev_b32_e32 v171, 16, v161
	ds_read_u16 v21, v25 offset:4352
	ds_read_u16 v161, v25 offset:4736
	v_mov_b32_e32 v163, v170
	v_pk_add_f32 v[162:163], v[162:163], v[170:171] neg_lo:[0,1] neg_hi:[0,1]
	s_waitcnt lgkmcnt(1)
	v_lshlrev_b32_e32 v174, 16, v21
	s_waitcnt lgkmcnt(0)
	v_lshlrev_b32_e32 v175, 16, v161
	ds_read_u16 v21, v25 offset:4480
	ds_read_u16 v161, v25 offset:4864
	v_mov_b32_e32 v167, v174
	v_pk_fma_f32 v[168:169], v[120:121], v[162:163], v[170:171] op_sel_hi:[0,1,1]
	v_pk_add_f32 v[162:163], v[166:167], v[174:175] neg_lo:[0,1] neg_hi:[0,1]
	s_waitcnt lgkmcnt(1)
	v_lshlrev_b32_e32 v188, 16, v21
	v_pk_fma_f32 v[166:167], v[224:225], v[162:163], v[174:175] op_sel_hi:[0,1,1]
	v_pk_add_f32 v[162:163], v[58:59], -1.0 op_sel_hi:[1,0]
	s_waitcnt lgkmcnt(0)
	v_lshlrev_b32_e32 v189, 16, v161
	v_pk_fma_f32 v[162:163], v[162:163], v[226:227], 1.0 op_sel_hi:[1,0,0]
	s_nop 0
	v_pk_mul_f32 v[162:163], v[162:163], v[166:167]
	v_pk_mul_f32 v[166:167], v[112:113], v[166:167] op_sel_hi:[0,1]
	v_pk_mul_f32 v[176:177], v[72:73], v[166:167]
	v_mul_f32_e32 v167, v11, v173
	v_mov_b32_e32 v166, v173
	v_pk_mul_f32 v[168:169], v[166:167], v[168:169]
	v_mul_f32_e32 v193, v12, v167
	v_mov_b32_e32 v192, v167
	v_rcp_f32_e32 v167, v167
	v_rcp_f32_e32 v166, v173
	v_pk_mul_f32 v[172:173], v[176:177], v[172:173] neg_lo:[0,1] neg_hi:[0,1]
	v_cvt_pk_bf16_f32 v161, v168, v169
	v_pk_mul_f32 v[168:169], v[58:59], v[176:177]
	v_cvt_pk_bf16_f32 v21, v172, v173
	v_pk_mul_f32 v[172:173], v[166:167], v[168:169]
	s_nop 0
	v_cvt_pk_bf16_f32 v170, v172, v173
	v_pk_mul_f32 v[172:173], v[166:167], v[162:163]
	s_nop 0
	v_cvt_pk_bf16_f32 v172, v172, v173
	ds_write_b16 v79, v21 offset:640
	ds_write_b16_d16_hi v79, v21 offset:704
	ds_write_b16 v79, v161 offset:2688
	ds_write_b16_d16_hi v79, v161 offset:2752
	ds_write_b16 v79, v170 offset:13184
	ds_write_b16_d16_hi v79, v170 offset:13248
	ds_write_b16 v79, v172 offset:15232
	ds_write_b16_d16_hi v79, v172 offset:15296
	ds_read_u16 v21, v25 offset:4992
	ds_read_u16 v161, v25 offset:5376
	v_mov_b32_e32 v172, v175
	v_mov_b32_e32 v170, v171
	s_waitcnt lgkmcnt(1)
	v_lshlrev_b32_e32 v180, 16, v21
	s_waitcnt lgkmcnt(0)
	v_lshlrev_b32_e32 v181, 16, v161
	ds_read_u16 v21, v25 offset:5120
	ds_read_u16 v161, v25 offset:5504
	v_mov_b32_e32 v171, v180
	v_pk_add_f32 v[170:171], v[170:171], v[180:181] neg_lo:[0,1] neg_hi:[0,1]
	s_waitcnt lgkmcnt(1)
	v_lshlrev_b32_e32 v178, 16, v21
	s_waitcnt lgkmcnt(0)
	v_lshlrev_b32_e32 v179, 16, v161
	ds_read_u16 v21, v25 offset:5248
	ds_read_u16 v161, v25 offset:5632
	v_mov_b32_e32 v173, v178
	v_pk_add_f32 v[172:173], v[172:173], v[178:179] neg_lo:[0,1] neg_hi:[0,1]
	s_waitcnt lgkmcnt(1)
	v_lshlrev_b32_e32 v190, 16, v21
	v_pk_fma_f32 v[174:175], v[224:225], v[172:173], v[178:179] op_sel_hi:[0,1,1]
	v_pk_add_f32 v[172:173], v[64:65], -1.0 op_sel_hi:[1,0]
	s_waitcnt lgkmcnt(0)
	v_lshlrev_b32_e32 v191, 16, v161
	v_pk_fma_f32 v[172:173], v[172:173], v[226:227], 1.0 op_sel_hi:[1,0,0]
	s_nop 0
	v_pk_mul_f32 v[172:173], v[172:173], v[174:175]
	v_pk_mul_f32 v[174:175], v[112:113], v[174:175] op_sel_hi:[0,1]
	v_pk_mul_f32 v[174:175], v[74:75], v[174:175]
	s_nop 0
	v_pk_mul_f32 v[176:177], v[174:175], v[192:193] neg_lo:[0,1] neg_hi:[0,1]
	v_pk_mul_f32 v[174:175], v[64:65], v[174:175]
	v_cvt_pk_bf16_f32 v21, v176, v177
	v_pk_fma_f32 v[176:177], v[120:121], v[170:171], v[180:181] op_sel_hi:[0,1,1]
	v_mul_f32_e32 v171, v13, v193
	v_mov_b32_e32 v170, v193
	v_pk_mul_f32 v[176:177], v[170:171], v[176:177]
	v_add_u32_e32 v180, s89, v196
	v_cvt_pk_bf16_f32 v161, v176, v177
	v_rcp_f32_e32 v176, v193
	v_rcp_f32_e32 v177, v171
	s_nop 0
	v_pk_mul_f32 v[192:193], v[176:177], v[174:175]
	s_nop 0
	v_cvt_pk_bf16_f32 v170, v192, v193
	v_pk_mul_f32 v[192:193], v[176:177], v[172:173]
	s_nop 0
	v_cvt_pk_bf16_f32 v178, v192, v193
	ds_write_b16 v79, v21 offset:768
	ds_write_b16_d16_hi v79, v21 offset:832
	ds_write_b16 v79, v161 offset:2816
	ds_write_b16_d16_hi v79, v161 offset:2880
	ds_write_b16 v79, v170 offset:13312
	ds_write_b16_d16_hi v79, v170 offset:13376
	ds_write_b16 v79, v178 offset:15360
	ds_write_b16_d16_hi v79, v178 offset:15424
	ds_read_u16 v21, v25 offset:6016
	ds_read_u16 v161, v25 offset:6400
	s_waitcnt lgkmcnt(1)
	v_lshlrev_b32_e32 v192, 16, v21
	s_waitcnt lgkmcnt(0)
	v_lshlrev_b32_e32 v193, 16, v161
	s_waitcnt vmcnt(0)
	v_pk_fma_f32 v[194:195], v[116:117], v[194:195], v[16:17] op_sel_hi:[0,1,1]
	v_mov_b32_e32 v16, v17
	v_mov_b32_e32 v17, v18
	v_pk_add_f32 v[16:17], v[16:17], v[18:19] neg_lo:[0,1] neg_hi:[0,1]
	s_nop 0
	v_pk_fma_f32 v[234:235], v[116:117], v[16:17], v[18:19] op_sel_hi:[0,1,1]
	v_mov_b32_e32 v16, v19
	v_mov_b32_e32 v17, v182
	v_pk_add_f32 v[16:17], v[16:17], v[182:183] neg_lo:[0,1] neg_hi:[0,1]
	s_nop 0
	v_pk_fma_f32 v[18:19], v[116:117], v[16:17], v[182:183] op_sel_hi:[0,1,1]
	v_mov_b32_e32 v16, v183
	v_mov_b32_e32 v17, v184
	v_pk_add_f32 v[16:17], v[16:17], v[184:185] neg_lo:[0,1] neg_hi:[0,1]
	v_cvt_pk_bf16_f32 v18, v18, v19
	v_pk_fma_f32 v[236:237], v[116:117], v[16:17], v[184:185] op_sel_hi:[0,1,1]
	v_mov_b32_e32 v16, v185
	v_mov_b32_e32 v17, v186
	v_pk_add_f32 v[16:17], v[16:17], v[186:187] neg_lo:[0,1] neg_hi:[0,1]
	v_cvt_pk_bf16_f32 v19, v236, v237
	v_pk_fma_f32 v[182:183], v[116:117], v[16:17], v[186:187] op_sel_hi:[0,1,1]
	v_mov_b32_e32 v16, v187
	v_mov_b32_e32 v17, v188
	v_pk_add_f32 v[16:17], v[16:17], v[188:189] neg_lo:[0,1] neg_hi:[0,1]
	s_nop 0
	v_pk_fma_f32 v[184:185], v[116:117], v[16:17], v[188:189] op_sel_hi:[0,1,1]
	v_mov_b32_e32 v16, v189
	v_mov_b32_e32 v17, v190
	v_pk_add_f32 v[16:17], v[16:17], v[190:191] neg_lo:[0,1] neg_hi:[0,1]
	s_nop 0
	v_pk_fma_f32 v[186:187], v[116:117], v[16:17], v[190:191] op_sel_hi:[0,1,1]
	v_mov_b32_e32 v16, v191
	v_mov_b32_e32 v17, v192
	v_pk_add_f32 v[16:17], v[16:17], v[192:193] neg_lo:[0,1] neg_hi:[0,1]
	s_nop 0
	v_pk_fma_f32 v[188:189], v[116:117], v[16:17], v[192:193] op_sel_hi:[0,1,1]
	ds_read_u16 v21, v25 offset:6272
	ds_read_u16 v161, v25 offset:6144
	ds_read_u16 v170, v25 offset:5760
	ds_read_u16 v178, v25 offset:5888
	v_cvt_pk_bf16_f32 v16, v194, v195
	v_cvt_pk_bf16_f32 v17, v234, v235
	ds_write_b128 v180, v[16:19] offset:10240
	v_cvt_pk_bf16_f32 v16, v182, v183
	v_cvt_pk_bf16_f32 v17, v184, v185
	v_cvt_pk_bf16_f32 v18, v186, v187
	v_cvt_pk_bf16_f32 v19, v188, v189
	ds_write_b128 v180, v[16:19] offset:10256
	s_waitcnt lgkmcnt(3)
; #define LAS __attribute__((address_space(3)))
; __device__ __forceinline__ unsigned pk2(float a, float b) { typedef __bf16 bf2_t __attribute__((ext_vector_type(2))); f32x2 v = {a, b}; return __builtin_bit_cast(unsigned, __builtin_convertvector(v, bf2_t)); }
; __device__ __forceinline__ void wy_issue(const Args& a, LAS unsigned char* stg, int b, int h, int c, int lane, float (&dec)[WY_T], float (&al)[WY_T], float (&rn)[WY_T]) {
;     ...
;     for (int j = 0; j < 7; ++j) { const int idx = j * 64 + lane;
;         if (idx < 408) { const int row = idx >> 3, trel = row / 3, vec = row - 3 * trel; size_t tk = tok0 + trel; tk = (tk == 0) ? 1 : tk;
;             __builtin_amdgcn_global_load_lds((const unsigned*)(PR + (tk - 1) * 1792 + vec * 512 + h * 64 + (idx & 7) * 8), (LAS unsigned*)(stg + j * 1024), 16, 0, 0); } }
; __device__ __forceinline__ void wy_build1(const Args& a, LAS unsigned char* slot, const LAS unsigned char* stg, int h, int c, int lane, const float (&dec)[WY_T], const float (&alr)[WY_T], const float (&rn)[WY_T]) {
;     ...
;     { u32x4 w0, w1; w0.x = pk2(vx[0], vx[1]); w0.y = pk2(vx[2], vx[3]); w0.z = pk2(vx[4], vx[5]); w0.w = pk2(vx[6], vx[7]); w1.x = pk2(vx[8], vx[9]); w1.y = pk2(vx[10], vx[11]); w1.z = pk2(vx[12], vx[13]); w1.w = pk2(vx[14], vx[15]);
;       *(LAS u32x4*)(slot + WY_VT + lane * 32) = w0; *(LAS u32x4*)(slot + WY_VT + lane * 32 + 16) = w1; }
;     *(LAS float*)(slot + WY_PT + lane * 4) = Pcum;
; #pragma unroll
;     for (int g = 0; g < 4; ++g) { float bh4[4], kh4[4];
; #pragma unroll
;         for (int j = 0; j < 4; ++j) { const float sc = Pcum * Pt[4 * g + j]; bh4[j] = bv[4 * g + j] * sc; kh4[j] = kv[4 * g + j] * sc; }
;         u32x4 w; w.x = pk2(bh4[0], bh4[1]); w.y = pk2(bh4[2], bh4[3]); w.z = pk2(kh4[0], kh4[1]); w.w = pk2(kh4[2], kh4[3]);
;         *(LAS u32x4*)(slot + WY_AS + (lane >> 4) * 1024 + (lane & 15) * 64 + g * 16) = w; }
	v_lshlrev_b32_e32 v16, 16, v170
	v_lshlrev_b32_e32 v17, 16, v161
	v_mov_b32_e32 v18, v181
	v_mov_b32_e32 v19, v16
	v_pk_add_f32 v[18:19], v[18:19], v[16:17] neg_lo:[0,1] neg_hi:[0,1]
	s_nop 0
	v_pk_fma_f32 v[180:181], v[120:121], v[18:19], v[16:17] op_sel_hi:[0,1,1]
	s_waitcnt lgkmcnt(2)
	v_lshlrev_b32_e32 v16, 16, v178
	v_lshlrev_b32_e32 v17, 16, v21
	v_mul_f32_e32 v21, v14, v171
	v_mov_b32_e32 v18, v179
	v_mov_b32_e32 v19, v16
	v_mul_f32_e32 v183, v15, v21
	v_pk_add_f32 v[18:19], v[18:19], v[16:17] neg_lo:[0,1] neg_hi:[0,1]
	v_mov_b32_e32 v78, v183
	v_pk_fma_f32 v[178:179], v[224:225], v[18:19], v[16:17] op_sel_hi:[0,1,1]
	v_pk_mul_f32 v[16:17], v[22:23], v[78:79] op_sel_hi:[1,0]
	v_pk_mul_f32 v[22:23], v[88:89], v[78:79] op_sel_hi:[1,0]
	v_pk_mul_f32 v[18:19], v[16:17], v[80:81]
	v_pk_mul_f32 v[16:17], v[16:17], v[86:87]
	v_pk_mul_f32 v[80:81], v[22:23], v[90:91]
	v_pk_mul_f32 v[22:23], v[22:23], v[92:93]
	v_cvt_pk_bf16_f32 v16, v16, v17
	v_cvt_pk_bf16_f32 v17, v22, v23
	v_cvt_pk_bf16_f32 v18, v18, v19
	v_cvt_pk_bf16_f32 v19, v80, v81
	ds_write_b128 v85, v[16:19] offset:6144
	v_pk_mul_f32 v[16:17], v[96:97], v[78:79] op_sel_hi:[1,0]
	v_pk_mul_f32 v[22:23], v[102:103], v[78:79] op_sel_hi:[1,0]
	v_pk_mul_f32 v[18:19], v[16:17], v[94:95]
	v_pk_mul_f32 v[16:17], v[16:17], v[98:99]
	v_pk_mul_f32 v[80:81], v[22:23], v[100:101]
	v_pk_mul_f32 v[22:23], v[22:23], v[104:105]
	v_cvt_pk_bf16_f32 v16, v16, v17
	v_cvt_pk_bf16_f32 v17, v22, v23
	v_cvt_pk_bf16_f32 v18, v18, v19
	v_cvt_pk_bf16_f32 v19, v80, v81
	ds_write_b128 v85, v[16:19] offset:6160
	v_pk_mul_f32 v[16:17], v[108:109], v[78:79] op_sel_hi:[1,0]
	v_pk_mul_f32 v[22:23], v[166:167], v[78:79] op_sel_hi:[1,0]
	v_pk_mul_f32 v[18:19], v[16:17], v[106:107]
	v_pk_mul_f32 v[16:17], v[16:17], v[110:111]
	v_pk_mul_f32 v[80:81], v[22:23], v[162:163]
	v_pk_mul_f32 v[22:23], v[22:23], v[168:169]
	v_rcp_f32_e32 v86, v21
	v_rcp_f32_e32 v87, v183
	v_cvt_pk_bf16_f32 v16, v16, v17
	v_cvt_pk_bf16_f32 v17, v22, v23
	v_cvt_pk_bf16_f32 v18, v18, v19
	v_cvt_pk_bf16_f32 v19, v80, v81
	ds_write_b128 v85, v[16:19] offset:6176
	v_pk_add_f32 v[16:17], v[76:77], -1.0 op_sel_hi:[1,0]
	v_pk_mul_f32 v[18:19], v[112:113], v[178:179] op_sel_hi:[0,1]
	v_pk_fma_f32 v[16:17], v[16:17], v[226:227], 1.0 op_sel_hi:[1,0,0]
	v_pk_mul_f32 v[88:89], v[36:37], v[18:19]
	v_pk_mul_f32 v[22:23], v[16:17], v[178:179]
	v_pk_mul_f32 v[16:17], v[176:177], v[78:79] op_sel_hi:[1,0]
	v_pk_mul_f32 v[90:91], v[78:79], v[86:87] op_sel_hi:[0,1]
	v_pk_mul_f32 v[92:93], v[76:77], v[88:89]
	v_pk_mul_f32 v[80:81], v[16:17], v[172:173]
	v_pk_mul_f32 v[16:17], v[16:17], v[174:175]
	v_pk_mul_f32 v[18:19], v[90:91], v[92:93]
	v_cvt_pk_bf16_f32 v16, v16, v17
	v_cvt_pk_bf16_f32 v17, v18, v19
	v_cvt_pk_bf16_f32 v18, v80, v81
	v_pk_mul_f32 v[80:81], v[90:91], v[22:23]
	v_mov_b32_e32 v20, v171
	v_cvt_pk_bf16_f32 v19, v80, v81
	ds_write_b128 v85, v[16:19] offset:6192
	v_mov_b32_e32 v182, v21
	v_pk_mul_f32 v[16:17], v[88:89], v[20:21] neg_lo:[0,1] neg_hi:[0,1]
	v_pk_mul_f32 v[18:19], v[86:87], v[92:93]
	v_pk_mul_f32 v[22:23], v[86:87], v[22:23]
	v_pk_mul_f32 v[80:81], v[182:183], v[180:181]
	v_add_u32_e32 v20, s89, v197
	v_cvt_pk_bf16_f32 v16, v16, v17
	ds_write_b32 v20, v183 offset:12288
	v_cvt_pk_bf16_f32 v17, v80, v81
	v_cvt_pk_bf16_f32 v18, v18, v19
	v_cvt_pk_bf16_f32 v19, v22, v23
	ds_write_b16 v79, v16 offset:896
	ds_write_b16_d16_hi v79, v16 offset:960
	ds_write_b16 v79, v17 offset:2944
	ds_write_b16_d16_hi v79, v17 offset:3008
	ds_write_b16 v79, v18 offset:13440
	ds_write_b16_d16_hi v79, v18 offset:13504
	ds_write_b16 v79, v19 offset:15488
	ds_write_b16_d16_hi v79, v19 offset:15552
	s_waitcnt lgkmcnt(0)
	s_cbranch_vccnz .LBB0_1428
	s_lshl_b64 s[0:1], s[84:85], 4
	s_add_u32 s96, s0, s28
	s_addc_u32 s97, s1, s29
	v_mov_b32_e32 v1, s97
	v_or_b32_e32 v0, s96, v122
	v_lshl_add_u64 v[2:3], v[0:1], 0, -1
	v_cmp_gt_u64_e32 vcc, v[2:3], v[0:1]
	s_mov_b32 m0, s88
	s_movk_i32 s6, 0xf200
	v_cndmask_b32_e64 v0, v2, 0, vcc
	v_mad_u64_u32 v[0:1], s[0:1], v0, s47, v[38:39]
	v_cndmask_b32_e64 v3, v3, 0, vcc
	v_mov_b32_e32 v2, v1
	v_mad_u64_u32 v[2:3], s[0:1], v3, s47, v[2:3]
	v_mov_b32_e32 v1, v2
	global_load_lds_dwordx4 v[0:1], off
	v_or_b32_e32 v0, s96, v126
	v_mad_u64_u32 v[0:1], s[0:1], v0, s47, v[48:49]
	v_mad_i32_i24 v1, s97, v227, v1
	s_mov_b32 s7, -1
	v_lshl_add_u64 v[0:1], v[0:1], 0, s[6:7]
	s_add_i32 m0, s88, 0x400
	s_nop 0
	global_load_lds_dwordx4 v[0:1], off
	v_or_b32_e32 v0, s96, v128
	v_mad_u64_u32 v[0:1], s[0:1], v0, s47, v[50:51]
	v_mad_i32_i24 v1, s97, v227, v1
	v_lshl_add_u64 v[0:1], v[0:1], 0, s[6:7]
	s_mov_b32 m0, s3
	s_nop 0
	global_load_lds_dwordx4 v[0:1], off
	v_or_b32_e32 v0, s96, v130
	v_mad_u64_u32 v[0:1], s[0:1], v0, s47, v[52:53]
	v_mad_i32_i24 v1, s97, v227, v1
	v_lshl_add_u64 v[0:1], v[0:1], 0, s[6:7]
	s_add_i32 m0, s88, 0xc00
	s_nop 0
	global_load_lds_dwordx4 v[0:1], off
	v_or_b32_e32 v0, s96, v132
	v_mad_u64_u32 v[0:1], s[0:1], v0, s47, v[54:55]
	v_mad_i32_i24 v1, s97, v227, v1
	v_lshl_add_u64 v[0:1], v[0:1], 0, s[6:7]
	s_add_i32 m0, s88, 0x1000
	s_nop 0
	global_load_lds_dwordx4 v[0:1], off
	v_or_b32_e32 v0, s96, v134
	v_mad_u64_u32 v[0:1], s[0:1], v0, s47, v[56:57]
	v_mad_i32_i24 v1, s97, v227, v1
	v_lshl_add_u64 v[0:1], v[0:1], 0, s[6:7]
	s_mov_b32 m0, s4
	s_nop 0
	global_load_lds_dwordx4 v[0:1], off
	s_and_saveexec_b64 s[0:1], s[76:77]
	s_cbranch_execz .LBB0_1427
	s_add_u32 s30, s96, 16
	s_addc_u32 s31, s97, 0
	s_add_u32 s34, s96, 15
	s_addc_u32 s35, s97, 0
	v_mov_b64_e32 v[0:1], s[30:31]
	v_cmp_gt_u64_e32 vcc, s[34:35], v[0:1]
	s_and_b64 s[30:31], vcc, exec
	s_cselect_b32 s5, 0, s34
	s_cselect_b32 s30, 0, s35
	s_mul_i32 s34, s30, 0xe00
	v_mad_u64_u32 v[0:1], s[30:31], s5, v227, v[136:137]
	v_add_u32_e32 v1, s34, v1
	s_mov_b32 s93, s85
	v_lshl_add_u64 v[0:1], v[0:1], 0, s[92:93]
	s_mov_b32 s6, 0xffff4000
	v_lshl_add_u64 v[0:1], v[0:1], 0, v[118:119]
	s_mov_b32 s7, -1
	v_lshl_add_u64 v[0:1], v[0:1], 0, s[6:7]
	s_add_i32 m0, s88, 0x1800
	s_nop 0
	global_load_lds_dwordx4 v[0:1], off

; #define LAS __attribute__((address_space(3)))
; #define WY_FENCE() do { asm volatile("s_waitcnt lgkmcnt(0)" ::: "memory"); __builtin_amdgcn_wave_barrier(); } while (0)
; __device__ __forceinline__ void wy_build2(LAS unsigned char* slot, int lane) {
;     ...
;     for (int s = 0; s < 2; ++s) { const bf16x8 fa = *(const LAS bf16x8*)(slot + WY_AZ + s * 1024 + fo), fr = *(const LAS bf16x8*)(slot + WY_AY1 + s * 1024 + fo), fb = *(const LAS bf16x8*)(scr + s * 1024 + fo), fk = *(const LAS bf16x8*)(scr + 2048 + s * 1024 + fo);
;         m1 = __builtin_amdgcn_mfma_f32_16x16x32_bf16(fa, fb, m1, 0, 0, 0); m2 = __builtin_amdgcn_mfma_f32_16x16x32_bf16(fa, fk, m2, 0, 0, 0);
;         m3 = __builtin_amdgcn_mfma_f32_16x16x32_bf16(fr, fb, m3, 0, 0, 0); m4 = __builtin_amdgcn_mfma_f32_16x16x32_bf16(fr, fk, m4, 0, 0, 0); }
;     WY_FENCE();
; #pragma unroll
;     for (int i = 0; i < 4; ++i) { const int t = 4 * g + i; const bool lo = row < t, le = row <= t;
;         *(LAS float*)(scr + (t * 16 + row) * 4) = lo ? m1[i] : 0.f; *(LAS float*)(scr + 1024 + (t * 16 + row) * 4) = lo ? m2[i] : 0.f;
;         *(LAS float*)(scr + 2048 + (t * 16 + row) * 4) = le ? m3[i] : 0.f; *(LAS float*)(scr + 3072 + (t * 16 + row) * 4) = le ? m4[i] : 0.f; }
;     WY_FENCE();
.LBB0_1428:
	v_add_u32_e32 v21, s89, v133
	ds_read_b128 v[16:19], v21
	ds_read_b128 v[86:89], v21 offset:12544
	ds_read_b128 v[98:101], v21 offset:2048
	ds_read_b128 v[102:105], v21 offset:1024
	ds_read_b128 v[94:97], v21 offset:14592
	v_readlane_b32 s0, v238, 20
	s_waitcnt lgkmcnt(0)
	v_mfma_f32_16x16x32_bf16 v[90:93], v[16:19], v[86:89], 0
	v_readlane_b32 s1, v238, 21
	ds_read_b128 v[106:109], v21 offset:15616
	v_mfma_f32_16x16x32_bf16 v[16:19], v[16:19], v[94:97], 0
	v_mfma_f32_16x16x32_bf16 v[86:89], v[98:101], v[86:89], 0
	v_mfma_f32_16x16x32_bf16 v[94:97], v[98:101], v[94:97], 0
	ds_read_b128 v[98:101], v21 offset:13568
	s_waitcnt lgkmcnt(0)
	v_mfma_f32_16x16x32_bf16 v[90:93], v[102:105], v[98:101], v[90:93]
	v_mfma_f32_16x16x32_bf16 v[16:19], v[102:105], v[106:109], v[16:19]
	ds_read_b128 v[102:105], v21 offset:3072
	s_nop 5
	v_cndmask_b32_e64 v21, 0, v90, s[64:65]
	s_waitcnt lgkmcnt(0)
	s_waitcnt lgkmcnt(0)
	v_mfma_f32_16x16x32_bf16 v[86:89], v[102:105], v[98:101], v[86:89]
	v_cndmask_b32_e64 v16, 0, v16, s[64:65]
	ds_write2st64_b32 v229, v21, v16 offset0:49 offset1:53
	v_cndmask_b32_e64 v17, v17, 0, s[54:55]
	v_mfma_f32_16x16x32_bf16 v[94:97], v[102:105], v[106:109], v[94:97]
	s_nop 3
	v_cndmask_b32_e64 v16, v86, 0, s[54:55]
	s_nop 2
	v_cndmask_b32_e64 v21, v94, 0, s[54:55]
	ds_write2st64_b32 v229, v16, v21 offset0:57 offset1:61
	v_cndmask_b32_e64 v16, v91, 0, s[54:55]
	ds_write2st64_b32 v230, v16, v17 offset0:49 offset1:53
	v_cndmask_b32_e64 v16, v87, 0, s[78:79]
	v_cndmask_b32_e64 v17, v95, 0, s[78:79]
	ds_write2st64_b32 v230, v16, v17 offset0:57 offset1:61
	v_cndmask_b32_e64 v16, 0, v92, s[0:1]
	v_cndmask_b32_e64 v17, 0, v18, s[0:1]
	v_readlane_b32 s0, v238, 22
	v_readlane_b32 s1, v238, 23
	ds_write2st64_b32 v231, v16, v17 offset0:49 offset1:53
	s_nop 0
	v_cndmask_b32_e64 v16, v88, 0, s[0:1]
	v_cndmask_b32_e64 v17, v96, 0, s[0:1]
	ds_write2st64_b32 v231, v16, v17 offset0:57 offset1:61
	v_cndmask_b32_e64 v16, 0, v93, s[58:59]
	v_cndmask_b32_e64 v17, 0, v19, s[58:59]
	ds_write2st64_b32 v232, v16, v17 offset0:49 offset1:53
	v_cndmask_b32_e64 v16, v89, 0, s[42:43]
	v_cndmask_b32_e64 v17, v97, 0, s[42:43]
	ds_write2st64_b32 v232, v16, v17 offset0:57 offset1:61
	s_waitcnt lgkmcnt(0)
	s_and_saveexec_b64 s[96:97], s[86:87]
	s_cbranch_execz .LBB0_1430
; #define LAS __attribute__((address_space(3)))
; __device__ __forceinline__ void wy_build2(LAS unsigned char* slot, int lane) {
;     ...
; #pragma unroll
;       for (int t = 1; t < WY_T; ++t) { float acc = x[t];
; #pragma unroll
;           for (int s4 = 0; s4 < (t + 3) / 4; ++s4) { const f32x4 mr = *(const LAS f32x4*)(scr + (t * 16 + 4 * s4) * 4);
; #pragma unroll
;               for (int e = 0; e < 4; ++e) if (4 * s4 + e < t) acc += mr[e] * x[4 * s4 + e]; }
;           x[t] = acc; }
;       if (lane < 16) {
; #pragma unroll
;           for (int t = 0; t < WY_T; ++t) *(LAS float*)(scr + 4096 + (t * 16 + row) * 4) = x[t]; } }
	v_mov_b32_e32 v80, s89
	ds_read_b128 v[96:99], v80 offset:12608
	ds_read_b128 v[100:103], v80 offset:12672
	ds_read_b128 v[104:107], v80 offset:12736
	ds_read_b128 v[108:111], v80 offset:12800
	ds_read_b128 v[166:169], v80 offset:12864
	ds_read_b128 v[170:173], v80 offset:12880
	ds_read_b128 v[174:177], v80 offset:12928
	ds_read_b128 v[178:181], v80 offset:12944
	ds_read_b128 v[182:185], v80 offset:12992
	ds_read_b128 v[186:189], v80 offset:13008
	ds_read_b128 v[190:193], v80 offset:13056
	ds_read_b128 v[234:237], v80 offset:13072
	s_waitcnt lgkmcnt(11)
	v_fma_f32 v22, v206, v96, v207
	ds_read_b128 v[96:99], v80 offset:13120
	s_waitcnt lgkmcnt(11)
	v_fma_f32 v23, v206, v100, v208
	v_fmac_f32_e32 v23, v101, v22
	ds_read_b128 v[100:103], v80 offset:13136
	s_waitcnt lgkmcnt(11)
	v_fma_f32 v78, v206, v104, v209
	v_fmac_f32_e32 v78, v105, v22
	v_fmac_f32_e32 v78, v106, v23
	ds_read_b128 v[104:107], v80 offset:13152
	s_waitcnt lgkmcnt(11)
	v_fma_f32 v81, v206, v108, v210
	v_fmac_f32_e32 v81, v109, v22
	v_fmac_f32_e32 v81, v110, v23
	v_fmac_f32_e32 v81, v111, v78
	ds_read_b128 v[108:111], v80 offset:13184
	s_waitcnt lgkmcnt(11)
	v_fma_f32 v82, v206, v166, v211
	v_fmac_f32_e32 v82, v167, v22
	v_fmac_f32_e32 v82, v168, v23
	v_fmac_f32_e32 v82, v169, v78
	s_waitcnt lgkmcnt(10)
	v_fmac_f32_e32 v82, v170, v81
	ds_read_b128 v[166:169], v80 offset:13200
	ds_read_b128 v[170:173], v80 offset:13216
	s_waitcnt lgkmcnt(11)
	v_fma_f32 v84, v206, v174, v212
	v_fmac_f32_e32 v84, v175, v22
	v_fmac_f32_e32 v84, v176, v23
	v_fmac_f32_e32 v84, v177, v78
	s_waitcnt lgkmcnt(10)
	v_fmac_f32_e32 v84, v178, v81
	v_fmac_f32_e32 v84, v179, v82
	ds_read_b128 v[174:177], v80 offset:13248
	ds_read_b128 v[178:181], v80 offset:13264
	s_waitcnt lgkmcnt(11)
	v_fma_f32 v86, v206, v182, v213
	v_fmac_f32_e32 v86, v183, v22
	v_fmac_f32_e32 v86, v184, v23
	v_fmac_f32_e32 v86, v185, v78
	s_waitcnt lgkmcnt(10)
	v_fmac_f32_e32 v86, v186, v81
	v_fmac_f32_e32 v86, v187, v82
	v_fmac_f32_e32 v86, v188, v84
	ds_read_b128 v[182:185], v80 offset:13280
	ds_read_b128 v[186:189], v80 offset:13312
	s_waitcnt lgkmcnt(11)
	v_fma_f32 v87, v206, v190, v214
	v_fmac_f32_e32 v87, v191, v22
	v_fmac_f32_e32 v87, v192, v23
	v_fmac_f32_e32 v87, v193, v78
	s_waitcnt lgkmcnt(10)
	v_fmac_f32_e32 v87, v234, v81
	v_fmac_f32_e32 v87, v235, v82
	v_fmac_f32_e32 v87, v236, v84
	v_fmac_f32_e32 v87, v237, v86
	ds_read_b128 v[190:193], v80 offset:13328
	ds_read_b128 v[234:237], v80 offset:13344
	s_waitcnt lgkmcnt(11)
	v_fma_f32 v88, v206, v96, v215
	v_fmac_f32_e32 v88, v97, v22
	v_fmac_f32_e32 v88, v98, v23
	v_fmac_f32_e32 v88, v99, v78
	s_waitcnt lgkmcnt(10)
	v_fmac_f32_e32 v88, v100, v81
	v_fmac_f32_e32 v88, v101, v82
	v_fmac_f32_e32 v88, v102, v84
	v_fmac_f32_e32 v88, v103, v86
	s_waitcnt lgkmcnt(9)
	v_fmac_f32_e32 v88, v104, v87
	ds_read_b128 v[96:99], v80 offset:13376
	ds_read_b128 v[100:103], v80 offset:13392
	ds_read_b128 v[104:107], v80 offset:13408
	s_waitcnt lgkmcnt(11)
	v_fma_f32 v89, v206, v108, v216
	v_fmac_f32_e32 v89, v109, v22
	v_fmac_f32_e32 v89, v110, v23
	v_fmac_f32_e32 v89, v111, v78
	s_waitcnt lgkmcnt(10)
	v_fmac_f32_e32 v89, v166, v81
	v_fmac_f32_e32 v89, v167, v82
	v_fmac_f32_e32 v89, v168, v84
	v_fmac_f32_e32 v89, v169, v86
	s_waitcnt lgkmcnt(9)
	v_fmac_f32_e32 v89, v170, v87
	v_fmac_f32_e32 v89, v171, v88
	ds_read_b128 v[108:111], v80 offset:13424
	ds_read_b128 v[166:169], v80 offset:13440
	ds_read_b128 v[170:173], v80 offset:13456
	s_waitcnt lgkmcnt(11)
	v_fma_f32 v90, v206, v174, v217
	v_fmac_f32_e32 v90, v175, v22
	v_fmac_f32_e32 v90, v176, v23
	v_fmac_f32_e32 v90, v177, v78
	s_waitcnt lgkmcnt(10)
	v_fmac_f32_e32 v90, v178, v81
	v_fmac_f32_e32 v90, v179, v82
	v_fmac_f32_e32 v90, v180, v84
	v_fmac_f32_e32 v90, v181, v86
	s_waitcnt lgkmcnt(9)
	v_fmac_f32_e32 v90, v182, v87
	v_fmac_f32_e32 v90, v183, v88
	v_fmac_f32_e32 v90, v184, v89
	ds_read_b128 v[174:177], v80 offset:13472
	ds_read_b128 v[178:181], v80 offset:13488
	ds_read_b128 v[182:185], v80 offset:13504
	s_waitcnt lgkmcnt(11)
	v_fma_f32 v19, v206, v186, v218
	v_fmac_f32_e32 v19, v187, v22
	v_fmac_f32_e32 v19, v188, v23
	v_fmac_f32_e32 v19, v189, v78
	s_waitcnt lgkmcnt(10)
	v_fmac_f32_e32 v19, v190, v81
	v_fmac_f32_e32 v19, v191, v82
	v_fmac_f32_e32 v19, v192, v84
	v_fmac_f32_e32 v19, v193, v86
	s_waitcnt lgkmcnt(9)
	v_fmac_f32_e32 v19, v234, v87
	v_fmac_f32_e32 v19, v235, v88
	v_fmac_f32_e32 v19, v236, v89
	v_fmac_f32_e32 v19, v237, v90
	ds_read_b128 v[186:189], v80 offset:13520
	ds_read_b128 v[190:193], v80 offset:13536
	ds_read_b128 v[234:237], v80 offset:13552
	s_waitcnt lgkmcnt(11)
	v_fma_f32 v16, v206, v96, v219
	v_fmac_f32_e32 v16, v97, v22
	v_fmac_f32_e32 v16, v98, v23
	v_fmac_f32_e32 v16, v99, v78
	s_waitcnt lgkmcnt(10)
	v_fmac_f32_e32 v16, v100, v81
	v_fmac_f32_e32 v16, v101, v82
	v_fmac_f32_e32 v16, v102, v84
	v_fmac_f32_e32 v16, v103, v86
	s_waitcnt lgkmcnt(9)
	v_fmac_f32_e32 v16, v104, v87
	v_fmac_f32_e32 v16, v105, v88
	v_fmac_f32_e32 v16, v106, v89
	v_fmac_f32_e32 v16, v107, v90
	s_waitcnt lgkmcnt(8)
	v_fmac_f32_e32 v16, v108, v19
	s_waitcnt lgkmcnt(7)
	v_fma_f32 v17, v206, v166, v220
	v_fmac_f32_e32 v17, v167, v22
	v_fmac_f32_e32 v17, v168, v23
	v_fmac_f32_e32 v17, v169, v78
	s_waitcnt lgkmcnt(6)
	v_fmac_f32_e32 v17, v170, v81
	v_fmac_f32_e32 v17, v171, v82
	v_fmac_f32_e32 v17, v172, v84
	v_fmac_f32_e32 v17, v173, v86
	s_waitcnt lgkmcnt(5)
	v_fmac_f32_e32 v17, v174, v87
	v_fmac_f32_e32 v17, v175, v88
	v_fmac_f32_e32 v17, v176, v89
	v_fmac_f32_e32 v17, v177, v90
	s_waitcnt lgkmcnt(4)
	v_fmac_f32_e32 v17, v178, v19
	v_fmac_f32_e32 v17, v179, v16
	s_waitcnt lgkmcnt(3)
	v_fma_f32 v21, v206, v182, v205
	v_fmac_f32_e32 v21, v183, v22
	v_fmac_f32_e32 v21, v184, v23
	v_fmac_f32_e32 v21, v185, v78
	s_waitcnt lgkmcnt(2)
	v_fmac_f32_e32 v21, v186, v81
	v_fmac_f32_e32 v21, v187, v82
	v_fmac_f32_e32 v21, v188, v84
	v_fmac_f32_e32 v21, v189, v86
	s_waitcnt lgkmcnt(1)
	v_fmac_f32_e32 v21, v190, v87
	v_fmac_f32_e32 v21, v191, v88
	v_fmac_f32_e32 v21, v192, v89
	v_fmac_f32_e32 v21, v193, v90
	s_waitcnt lgkmcnt(0)
	v_fmac_f32_e32 v21, v234, v19
	v_fmac_f32_e32 v21, v235, v16
	v_fmac_f32_e32 v21, v236, v17
	v_add_u32_e32 v18, 0x4000, v20
	ds_write2_b32 v18, v206, v22 offset0:64 offset1:80
	ds_write2_b32 v18, v23, v78 offset0:96 offset1:112
	ds_write2_b32 v18, v81, v82 offset0:128 offset1:144
	ds_write2_b32 v18, v84, v86 offset0:160 offset1:176
	ds_write2_b32 v18, v87, v88 offset0:192 offset1:208
	ds_write2_b32 v18, v89, v90 offset0:224 offset1:240
	v_add_u32_e32 v18, 0x4400, v20
	ds_write2_b32 v18, v19, v16 offset1:16
	ds_write2_b32 v18, v17, v21 offset0:32 offset1:48
